# P3 queue: NSA items of each group handed out before its MLA items (cheapest items at the tail)
# speedup vs baseline: 1.0081x; 1.0081x over previous
; #define SCHED_BARRIER() __builtin_amdgcn_sched_barrier(0)
; __global__ void __launch_bounds__(512) mega(Params p) {
;     ...
; #pragma unroll 1
;       for (int grp = 0; grp < 8; ++grp) {
;         const int base = 80 + grp * 144;
;         while (it < base + 80) { const int r = it - base; mla_item(cx, r / 5, r % 5, 7 - grp, lds, wv); it = next_item(ctr, slot, wv) - 32; }
;         SCHED_BARRIER();
;         while (it < base + 144) { const int r = it - base - 80; const int e = r & 31; nsa_item(cx, cflag, e >> 1, e & 1, (r < 32 ? 15 : 14) - 2 * grp, lds, wv); it = next_item(ctr, slot, wv) - 32; }
.LBB0_1348:
	v_readlane_b32 s0, v255, 6
	s_branch .Lq_mla_check

; __global__ void __launch_bounds__(512) mega(Params p) {
;     ...
;       for (int grp = 0; grp < 8; ++grp) {
;         const int base = 80 + grp * 144;
;         while (it < base + 80) { const int r = it - base; mla_item(cx, r / 5, r % 5, 7 - grp, lds, wv); it = next_item(ctr, slot, wv) - 32; }
.LBB0_1350:
	s_mul_i32 s2, s0, 0x90
	s_mov_b32 s86, s2
	s_branch .Lq_nsa_check
.Lq_mla_check:
	s_mul_i32 s2, s0, 0x90
	s_add_i32 s86, s2, 0x90
	s_add_i32 s3, s2, 0xe0
	s_cmp_ge_i32 s8, s3
	s_cbranch_scc1 .LBB0_1349
	s_mov_b32 s24, s0
	s_sub_i32 s0, 7, s0
	s_lshl_b32 s15, s0, 2
	s_lshl_b32 s14, s0, 8
	s_add_i32 s15, s15, 4
	s_branch .LBB0_1354

; #define SCHED_BARRIER() __builtin_amdgcn_sched_barrier(0)
; __global__ void __launch_bounds__(512) mega(Params p) {
;     ...
;         SCHED_BARRIER();
;         while (it < base + 144) { const int r = it - base - 80; const int e = r & 31; nsa_item(cx, cflag, e >> 1, e & 1, (r < 32 ? 15 : 14) - 2 * grp, lds, wv); it = next_item(ctr, slot, wv) - 32; }
.LBB0_1391:
	s_mov_b32 s0, s24
	s_branch .LBB0_1349
.Lq_nsa_check:
	s_add_i32 s1, s2, 0x90
	v_writelane_b32 v255, s1, 15
	s_cmp_ge_i32 s8, s1
	s_cbranch_scc1 .Lq_mla_check
	v_writelane_b32 v255, s0, 6
	s_lshl_b32 s0, s0, 1
	v_writelane_b32 v255, s0, 19
	s_branch .LBB0_1396
